# PRO x-row loop: the two WAR-only waits removed (all 8 row loads of an iteration issue back to back; previous iteration's stores no longer drained before the loads)
# baseline (speedup 1.0000x reference)
.LBB0_649:
	s_mov_b32 s6, 0x8000
	v_add_u32_e32 v0, 0xffff8000, v38
	v_cmp_gt_i32_e32 vcc, s6, v38
	v_ashrrev_i32_e32 v39, 31, v38
	v_mov_b32_e32 v4, s53
	s_waitcnt lgkmcnt(0)
	v_cndmask_b32_e32 v2, v0, v38, vcc
	v_mov_b32_e32 v0, s55
	s_waitcnt lgkmcnt(0)
	v_cndmask_b32_e32 v3, 0, v39, vcc
	v_cndmask_b32_e32 v5, v0, v4, vcc
	v_mov_b32_e32 v0, s54
	v_mov_b32_e32 v4, s52
	v_cndmask_b32_e32 v4, v0, v4, vcc
	v_lshlrev_b64 v[2:3], 12, v[2:3]
	v_lshl_add_u64 v[2:3], v[4:5], 0, v[2:3]
	v_lshlrev_b32_e32 v0, 2, v34
	v_cmp_ne_u64_e32 vcc, 0, v[4:5]
	v_lshl_add_u64 v[2:3], v[2:3], 0, v[0:1]
	v_mov_b32_e32 v14, 0
	v_mov_b32_e32 v26, 0
	v_mov_b32_e32 v27, 0
	v_mov_b32_e32 v28, 0
	v_mov_b32_e32 v29, 0
	s_and_saveexec_b64 s[40:41], vcc
	s_cbranch_execz .LBB0_651
	global_load_dwordx4 v[26:29], v[2:3], off

.LBB0_665:
	s_or_b64 exec, exec, s[44:45]
	v_mov_b32_e32 v6, 0
	v_mov_b32_e32 v18, 0
	v_mov_b32_e32 v19, 0
	v_mov_b32_e32 v20, 0
	v_mov_b32_e32 v21, 0
	s_and_saveexec_b64 s[44:45], s[42:43]
	s_cbranch_execz .LBB0_667
	global_load_dwordx4 v[18:21], v[42:43], off offset:2048
